# MLA loop: QK/PV MFMAs interleaved with softmax VALU; V^T stored tile-pair-major (contiguous 16 KB per 128 keys) instead of 16 KB-strided rows
# speedup vs baseline: 1.0002x; 1.0002x over previous
; #define LAS __attribute__((address_space(3)))
; __device__ __forceinline__ unsigned pk4_fp8(float a, float b, float c, float d) { int p = __builtin_amdgcn_cvt_pk_fp8_f32(a, b, 0, false); p = __builtin_amdgcn_cvt_pk_fp8_f32(c, d, p, true); return (unsigned)p; }
;     __device__ __forceinline__ void operator()(const Acc& acc, const Unit& u, int wr, int wc, int fr, int fq) const {
;     ...
;                 const f32x4 k0 = acc[ai][0][m][0] * s, k1 = acc[ai][0][m][1] * s;
;                 u32x2 w; w.x = pk4_fp8(k0[0], k0[1], k0[2], k0[3]); w.y = pk4_fp8(k1[0], k1[1], k1[2], k1[3]);
;                 *(u32x2*)((char*)kvb + (size_t)row * (LDKVB * 2) + (size_t)(u.pn - 5) * 512 + wc * 32 + 8 * fq) = w;
;                 const f32x4 v0 = acc[ai][1][m][0] * s, v1 = acc[ai][1][m][1] * s; const unsigned q0 = pk4_fp8(v0[0], v0[1], v0[2], v0[3]), q1 = pk4_fp8(v1[0], v1[1], v1[2], v1[3]);
;                 LAS unsigned char* sp = ldsx + 131072 + (wr * 4 + wc) * 2048 + (8 * fq) * 64 + 16 * m + fr;
;                 sp[0 * 64] = (unsigned char)(q0); sp[1 * 64] = (unsigned char)(q0 >> 8); sp[2 * 64] = (unsigned char)(q0 >> 16); sp[3 * 64] = (unsigned char)(q0 >> 24);
;                 sp[4 * 64] = (unsigned char)(q1); sp[5 * 64] = (unsigned char)(q1 >> 8); sp[6 * 64] = (unsigned char)(q1 >> 16); sp[7 * 64] = (unsigned char)(q1 >> 24);
;                 if (m == 3) {
;                     asm volatile("s_waitcnt lgkmcnt(0)" ::: "memory");
;                     const int pm = u.pm, sq = pm < 64 ? 0 : (pm < 128 ? 1 : 2), slen = sq < 2 ? SEQ_P : SEQ_S, pos0 = pm * 256 - (sq < 2 ? sq * SEQ_P : T_PROMPT);
;                     unsigned char* vth = vt + (size_t)sq * (6 * 128 * SEQ_P) + (size_t)(u.pn - 5) * 128 * slen;
;                     const int lane_ = fq * 16 + fr; LAS unsigned char* wb = ldsx + 131072 + (wr * 4 + wc) * 2048;
; #pragma unroll
;                     for (int c2 = 0; c2 < 2; ++c2) { const int id = lane_ + 64 * c2, col = id >> 2, seg = id & 3;
;                         const u32x4 vv = *(const LAS u32x4*)(wb + col * 64 + seg * 16);
;                         *(u32x4*)(vth + (size_t)(32 * wc + col) * slen + pos0 + ai * HALF + wr * 64 + seg * 16) = vv; }
;                     asm volatile("s_waitcnt lgkmcnt(0)" ::: "memory");
.LBB0_374:
	v_or_b32_e32 v85, 48, v167
	s_nop 0
	v_lshl_or_b32 v80, v85, 1, s21
	v_ashrrev_i32_e32 v81, 31, v80
	v_lshl_add_u64 v[80:81], v[80:81], 2, s[68:69]
	global_load_dword v84, v[80:81], off
	s_cmpk_lt_i32 s57, 0x80
	s_cselect_b32 s34, 1, 2
	s_cmp_gt_i32 s57, 63
	s_cselect_b32 s34, s34, 0
	s_lshl_b32 s35, s34, 14
	s_cmpk_lt_i32 s57, 0x80
	s_cselect_b32 s35, s35, 0x8000
	s_cselect_b32 s58, 14, 13
	s_sub_i32 s31, s31, s35
	s_mul_i32 s57, s34, 0xc00000
	s_lshl_b64 s[34:35], s[10:11], 7
	s_lshl_b64 s[34:35], s[34:35], s58
	s_lshl_b32 s10, s31, 7
	s_mov_b64 s[36:37], -1
	s_and_b64 vcc, exec, s[8:9]
	v_lshlrev_b64 v[82:83], 7, v[140:141]
	v_lshlrev_b64 v[80:81], 7, v[142:143]
	s_cbranch_vccnz .LBB0_376
	s_waitcnt vmcnt(0)
	v_pk_mul_f32 v[86:87], v[76:77], v[84:85] op_sel_hi:[1,0]
	v_mov_b32_e32 v90, 0
	v_pk_mul_f32 v[88:89], v[72:73], v[84:85] op_sel_hi:[1,0]
	v_cvt_pk_fp8_f32 v90, v86, v87
	v_mov_b32_e32 v91, 0
	v_cvt_pk_fp8_f32 v91, v88, v89
	v_pk_mul_f32 v[86:87], v[78:79], v[84:85] op_sel_hi:[1,0]
	v_pk_mul_f32 v[92:93], v[68:69], v[84:85] op_sel_hi:[1,0]
	v_mov_b32_e32 v94, 0
	v_pk_mul_f32 v[88:89], v[74:75], v[84:85] op_sel_hi:[1,0]
	v_cvt_pk_fp8_f32 v90, v86, v87 op_sel:[0,0,1]
	v_mov_b64_e32 v[86:87], s[74:75]
	v_cvt_pk_fp8_f32 v94, v92, v93
	v_cvt_pk_fp8_f32 v91, v88, v89 op_sel:[0,0,1]
	v_mad_i64_i32 v[86:87], s[36:37], v85, s38, v[86:87]
	v_pk_mul_f32 v[92:93], v[64:65], v[84:85] op_sel_hi:[1,0]
	v_mov_b32_e32 v95, 0
	v_lshl_add_u64 v[86:87], v[86:87], 0, s[28:29]
	v_cvt_pk_fp8_f32 v95, v92, v93
	v_lshl_add_u64 v[86:87], v[86:87], 0, s[14:15]
	v_pk_mul_f32 v[88:89], v[70:71], v[84:85] op_sel_hi:[1,0]
	v_lshl_add_u64 v[86:87], v[86:87], 0, v[136:137]
	v_cvt_pk_fp8_f32 v94, v88, v89 op_sel:[0,0,1]
	global_store_dwordx2 v[86:87], v[90:91], off
	v_pk_mul_f32 v[86:87], v[66:67], v[84:85] op_sel_hi:[1,0]
	s_add_u32 s36, s76, s57
	v_cvt_pk_fp8_f32 v95, v86, v87 op_sel:[0,0,1]
	v_lshrrev_b32_e32 v86, 8, v94
	ds_write_b8 v164, v94
	ds_write_b8 v164, v86 offset:64
	ds_write_b8_d16_hi v164, v94 offset:128
	v_lshrrev_b32_e32 v86, 24, v94
	ds_write_b8 v164, v86 offset:192
	ds_write_b8 v164, v95 offset:256
	v_lshrrev_b32_e32 v86, 8, v95
	s_addc_u32 s37, s77, 0
	ds_write_b8 v164, v86 offset:320
	ds_write_b8_d16_hi v164, v95 offset:384
	v_lshrrev_b32_e32 v86, 24, v95
	s_add_u32 s36, s36, s34
	ds_write_b8 v164, v86 offset:448
	s_addc_u32 s37, s37, s35
	s_waitcnt lgkmcnt(0)
	s_add_u32 s36, s36, s10
	s_addc_u32 s37, s37, 0
	ds_read_b128 v[86:89], v165
	ds_read_b128 v[90:93], v166
	s_add_u32 s36, s36, s44
	s_addc_u32 s37, s37, s48
	v_lshl_add_u64 v[94:95], s[36:37], 0, v[138:139]
	v_lshl_add_u64 v[96:97], v[94:95], 0, v[82:83]
	s_waitcnt lgkmcnt(1)
	global_store_dwordx4 v[96:97], v[86:89], off
	s_mov_b64 s[36:37], 0
	s_nop 0
	v_lshl_add_u64 v[86:87], v[94:95], 0, v[80:81]
	s_waitcnt lgkmcnt(0)
	global_store_dwordx4 v[86:87], v[90:93], off
	s_waitcnt lgkmcnt(0)

; #define LAS __attribute__((address_space(3)))
; __device__ __forceinline__ unsigned pk4_fp8(float a, float b, float c, float d) { int p = __builtin_amdgcn_cvt_pk_fp8_f32(a, b, 0, false); p = __builtin_amdgcn_cvt_pk_fp8_f32(c, d, p, true); return (unsigned)p; }
;     __device__ __forceinline__ void operator()(const Acc& acc, const Unit& u, int wr, int wc, int fr, int fq) const {
;     ...
;                 const f32x4 k0 = acc[ai][0][m][0] * s, k1 = acc[ai][0][m][1] * s;
;                 u32x2 w; w.x = pk4_fp8(k0[0], k0[1], k0[2], k0[3]); w.y = pk4_fp8(k1[0], k1[1], k1[2], k1[3]);
;                 *(u32x2*)((char*)kvb + (size_t)row * (LDKVB * 2) + (size_t)(u.pn - 5) * 512 + wc * 32 + 8 * fq) = w;
;                 const f32x4 v0 = acc[ai][1][m][0] * s, v1 = acc[ai][1][m][1] * s; const unsigned q0 = pk4_fp8(v0[0], v0[1], v0[2], v0[3]), q1 = pk4_fp8(v1[0], v1[1], v1[2], v1[3]);
;                 LAS unsigned char* sp = ldsx + 131072 + (wr * 4 + wc) * 2048 + (8 * fq) * 64 + 16 * m + fr;
;                 sp[0 * 64] = (unsigned char)(q0); sp[1 * 64] = (unsigned char)(q0 >> 8); sp[2 * 64] = (unsigned char)(q0 >> 16); sp[3 * 64] = (unsigned char)(q0 >> 24);
;                 sp[4 * 64] = (unsigned char)(q1); sp[5 * 64] = (unsigned char)(q1 >> 8); sp[6 * 64] = (unsigned char)(q1 >> 16); sp[7 * 64] = (unsigned char)(q1 >> 24);
;                 if (m == 3) {
;                     asm volatile("s_waitcnt lgkmcnt(0)" ::: "memory");
;                     const int pm = u.pm, sq = pm < 64 ? 0 : (pm < 128 ? 1 : 2), slen = sq < 2 ? SEQ_P : SEQ_S, pos0 = pm * 256 - (sq < 2 ? sq * SEQ_P : T_PROMPT);
;                     unsigned char* vth = vt + (size_t)sq * (6 * 128 * SEQ_P) + (size_t)(u.pn - 5) * 128 * slen;
;                     const int lane_ = fq * 16 + fr; LAS unsigned char* wb = ldsx + 131072 + (wr * 4 + wc) * 2048;
; #pragma unroll
;                     for (int c2 = 0; c2 < 2; ++c2) { const int id = lane_ + 64 * c2, col = id >> 2, seg = id & 3;
;                         const u32x4 vv = *(const LAS u32x4*)(wb + col * 64 + seg * 16);
;                         *(u32x4*)(vth + (size_t)(32 * wc + col) * slen + pos0 + ai * HALF + wr * 64 + seg * 16) = vv; }
;                     asm volatile("s_waitcnt lgkmcnt(0)" ::: "memory");
.LBB0_390:
	s_nop 1
	v_add_u32_e32 v17, 0xb0, v167
	v_lshl_or_b32 v18, v17, 1, s21
	v_ashrrev_i32_e32 v19, 31, v18
	v_lshl_add_u64 v[18:19], v[18:19], 2, s[68:69]
	global_load_dword v16, v[18:19], off
	s_and_b64 vcc, exec, s[8:9]
	s_mov_b64 s[8:9], -1
	s_cbranch_vccnz .LBB0_393
	s_waitcnt vmcnt(0)
	v_pk_mul_f32 v[18:19], v[12:13], v[16:17] op_sel_hi:[1,0]
	v_mov_b32_e32 v22, 0
	v_pk_mul_f32 v[20:21], v[8:9], v[16:17] op_sel_hi:[1,0]
	v_cvt_pk_fp8_f32 v22, v18, v19
	v_mov_b32_e32 v23, 0
	v_cvt_pk_fp8_f32 v23, v20, v21
	v_pk_mul_f32 v[18:19], v[14:15], v[16:17] op_sel_hi:[1,0]
	v_pk_mul_f32 v[24:25], v[4:5], v[16:17] op_sel_hi:[1,0]
	v_mov_b32_e32 v26, 0
	v_pk_mul_f32 v[20:21], v[10:11], v[16:17] op_sel_hi:[1,0]
	v_cvt_pk_fp8_f32 v22, v18, v19 op_sel:[0,0,1]
	v_mov_b64_e32 v[18:19], s[74:75]
	v_cvt_pk_fp8_f32 v26, v24, v25
	v_cvt_pk_fp8_f32 v23, v20, v21 op_sel:[0,0,1]
	v_mad_i64_i32 v[18:19], s[8:9], v17, s38, v[18:19]
	v_pk_mul_f32 v[24:25], v[0:1], v[16:17] op_sel_hi:[1,0]
	v_mov_b32_e32 v27, 0
	v_lshl_add_u64 v[18:19], v[18:19], 0, s[28:29]
	v_cvt_pk_fp8_f32 v27, v24, v25
	v_lshl_add_u64 v[18:19], v[18:19], 0, s[14:15]
	v_pk_mul_f32 v[20:21], v[6:7], v[16:17] op_sel_hi:[1,0]
	v_lshl_add_u64 v[18:19], v[18:19], 0, v[136:137]
	v_cvt_pk_fp8_f32 v26, v20, v21 op_sel:[0,0,1]
	global_store_dwordx2 v[18:19], v[22:23], off
	v_pk_mul_f32 v[18:19], v[2:3], v[16:17] op_sel_hi:[1,0]
	s_add_u32 s8, s76, s57
	v_cvt_pk_fp8_f32 v27, v18, v19 op_sel:[0,0,1]
	v_lshrrev_b32_e32 v18, 8, v26
	ds_write_b8 v164, v26
	ds_write_b8 v164, v18 offset:64
	ds_write_b8_d16_hi v164, v26 offset:128
	v_lshrrev_b32_e32 v18, 24, v26
	ds_write_b8 v164, v18 offset:192
	ds_write_b8 v164, v27 offset:256
	v_lshrrev_b32_e32 v18, 8, v27
	s_addc_u32 s9, s77, 0
	ds_write_b8 v164, v18 offset:320
	ds_write_b8_d16_hi v164, v27 offset:384
	v_lshrrev_b32_e32 v18, 24, v27
	s_add_u32 s8, s8, s34
	ds_write_b8 v164, v18 offset:448
	s_addc_u32 s9, s9, s35
	s_waitcnt lgkmcnt(0)
	s_add_u32 s8, s8, s10
	s_addc_u32 s9, s9, 0
	ds_read_b128 v[18:21], v165
	ds_read_b128 v[22:25], v166
	s_add_u32 s8, s8, s44
	s_addc_u32 s9, s9, s48
	s_add_u32 s8, s8, 0x4000
	s_addc_u32 s9, s9, 0
	v_lshl_add_u64 v[26:27], s[8:9], 0, v[138:139]
	v_lshl_add_u64 v[28:29], v[26:27], 0, v[82:83]
	s_waitcnt lgkmcnt(1)
	global_store_dwordx4 v[28:29], v[18:21], off
	s_nop 1
	v_lshl_add_u64 v[18:19], v[26:27], 0, v[80:81]
	s_waitcnt lgkmcnt(0)
	global_store_dwordx4 v[18:19], v[22:25], off
	s_waitcnt lgkmcnt(0)
	s_cbranch_execz .LBB0_394

; __global__ void __launch_bounds__(512) fwd_megakernel(Args args) {
;     ...
;             if (u < 960) {
;                 int sq, h, qb, len, rowbase;
;                 if (u < 768) { sq = u / 384; const int rem = u % 384; h = rem / 64; qb = rem % 64; len = SEQ_P; rowbase = sq * SEQ_P; }
;                 else { const int v = u - 768; h = v / 32; qb = v % 32; len = SEQ_S; rowbase = T_PROMPT; }
;                 const long q0 = (long)rowbase + qb * 256;
;                 att::attn_body<0, 1>(QB + q0 * LDQB + h * 192, (const bf16_t*)((const char*)KVB + (long)rowbase * (LDKVB * 2) + h * 512)  , (const bf16_t*)((const char*)args.out + (size_t)T_TOK * NPROJ * 2 + (size_t)(rowbase / SEQ_P) * (6 * 128 * SEQ_P) + (size_t)h * 128 * len)  , (const bf16_t*)((const char*)KROPE + (long)rowbase * 64)  ,
;                                      AOUT + q0 * DM + 768 + h * 128, len / 64, 0.07216878364870322f * LOG2E, ROPE + (long)qb * 256 * 32, 0, 0.f, false, LDQB, len, DM, shm);
;             } else {
;                 const bf16_t *Qp, *Kp, *Vp; bf16_t* Op; int NT, kbw, ldk, ldo; float sink; bool nomask;
;                 if (u < 1920) {
;                     const int v = u - 960, t256 = v / 6, h = v % 6, kvh = h / 3;
;                     const long q0 = (long)t256 * 256;
;                     const int rowbase = q0 < T_PROMPT ? (int)(q0 & ~(long)(SEQ_P - 1)) : T_PROMPT; const int len = q0 < T_PROMPT ? SEQ_P : SEQ_S;
;                     const int ql = (int)(q0 - rowbase);
;                     const int ks = ql - 128 < 0 ? 0 : ql - 128; const int ke = ql + 384 > len ? len : ql + 384;
;                     if (tid < 257) { const int rel = tid - 128; const int n = rel < 0 ? -rel : rel;
;                         const int large = 8 + (n >= 12) + (n >= 16) + (n >= 23) + (n >= 32) + (n >= 46) + (n >= 64) + (n >= 91);
;                         const int bucket = (rel > 0 ? 16 : 0) + (n < 8 ? n : large);
;                         btab[tid] = args.in[5][bucket * 6 + h] * LOG2E; }
;                     const long k0 = (long)rowbase + ks;
;                     Qp = PROJ + q0 * NPROJ + C_QA + h * 128; Kp = PROJ + k0 * NPROJ + C_KA + kvh * 128; Vp = PROJ + k0 * NPROJ + C_VA + kvh * 128; Op = AOUT + q0 * DM + h * 128;
;                     NT = (ke - ks) / 64; kbw = ks - ql + 128; ldk = NPROJ; ldo = DM; sink = args.in[6][h] * LOG2E; nomask = false;
.LBB0_450:
	v_writelane_b32 v255, s83, 7
	v_writelane_b32 v255, s82, 8
	v_writelane_b32 v255, s78, 9
	s_nop 1
	v_writelane_b32 v255, s79, 10
	s_or_b64 exec, exec, s[6:7]
	s_waitcnt lgkmcnt(0)
	v_subrev_co_u32_e32 v0, vcc, 0x80, v190
	s_mov_b64 s[8:9], vcc
	v_sub_co_u32_e32 v1, vcc, 0x80, v190
	v_cndmask_b32_e64 v0, v0, v1, s[8:9]
	v_cmp_lt_u32_e64 s[8:9], 11, v0
	s_movk_i32 s47, 0x101
	v_cmp_gt_u32_e64 s[0:1], s47, v190
	v_cndmask_b32_e64 v1, 8, 9, s[8:9]
	v_cmp_lt_u32_e64 s[8:9], 15, v0
	v_writelane_b32 v255, s0, 11
	s_nop 0
	v_cndmask_b32_e64 v2, 0, 1, s[8:9]
	v_cmp_lt_u32_e64 s[8:9], 22, v0
	v_writelane_b32 v255, s1, 12
	s_movk_i32 s0, 0x5a
	v_addc_co_u32_e64 v1, s[8:9], v1, v2, s[8:9]
	v_cmp_lt_u32_e64 s[8:9], 31, v0
	s_barrier
	s_nop 0
	v_cndmask_b32_e64 v2, 0, 1, s[8:9]
	v_cmp_lt_u32_e64 s[8:9], 45, v0
	v_writelane_b32 v255, s80, 13
	s_mov_b64 s[78:79], src_shared_base
	v_addc_co_u32_e64 v1, s[8:9], v1, v2, s[8:9]
	v_cmp_lt_u32_e64 s[8:9], 63, v0
	v_writelane_b32 v255, s81, 14
	s_movk_i32 s92, 0xff80
	v_cndmask_b32_e64 v2, 0, 1, s[8:9]
	v_cmp_lt_u32_e64 s[8:9], s0, v0
	s_add_i32 s0, 0, 0x1c800
	s_add_u32 s82, s54, 0x8500000
	v_addc_co_u32_e64 v1, s[8:9], v1, v2, s[8:9]
	s_load_dwordx4 s[8:11], s[80:81], 0x28
	s_addc_u32 s83, s55, 0
	s_add_u32 s86, s54, 0x7e00000
	s_addc_u32 s87, s55, 0
	s_add_u32 s84, s54, 0x37260000
	s_waitcnt lgkmcnt(0)
	v_writelane_b32 v255, s8, 15
	s_addc_u32 s85, s55, 0
	v_lshl_add_u32 v215, v190, 2, s0
	v_writelane_b32 v255, s9, 16
	v_writelane_b32 v255, s10, 17
	s_add_u32 s0, s62, 0xf004000
	v_cndmask_b32_e64 v2, 0, 16, vcc
	v_cmp_gt_u32_e32 vcc, 8, v0
	v_writelane_b32 v255, s11, 18
	s_addc_u32 s1, s63, 0
	v_cndmask_b32_e32 v0, v1, v0, vcc
	v_writelane_b32 v255, s0, 19
	v_add_u32_e32 v0, v0, v2
	v_mul_lo_u32 v214, v0, 6
	v_writelane_b32 v255, s1, 20
	s_add_i32 s0, 0, 0x1cc04
	s_mov_b64 s[88:89], 0
	v_mov_b32_e32 v1, 0
	s_add_i32 s53, 0, 0x1cc80
	s_movk_i32 s56, 0xa00
	v_writelane_b32 v255, s0, 21
	s_add_i32 s91, 0, 0x14000
	s_mov_b32 s6, 0x41380000
	s_mov_b32 s7, 0x2aaaaaab
	s_movk_i32 s0, 0xc00
	s_mov_b32 s1, 0xc00000
	s_movk_i32 s90, 0xd0
	v_mov_b32_e32 v216, 0x7f7f7f7f
	s_mov_b32 s78, 0x3dd53b94
	s_mov_b32 s57, 0x40f00000
	s_mov_b32 s93, -1
	s_mov_b64 s[94:95], 0x60000
	v_mov_b32_e32 v218, 0x4000
	v_mov_b32_e32 v219, 0x100
	v_mov_b32_e32 v220, 0x80000
	v_mov_b32_e32 v221, 0x101
	v_mov_b32_e32 v222, 0xf149f2ca
	s_branch .LBB0_454

; template <int MODE, int SD> ...
;   int tid = threadIdx.x; asm volatile("" : "+v"(tid));
;   const int wid = tid >> 6, lane = tid & 63, r32 = lane & 31, hi = lane >> 5;
;   if (ATT_PRIO && wid >= 4) __builtin_amdgcn_s_setprio(1);
;   char* V_lds = lds + OFF_V; char* K_lds = lds + OFF_K; char* Kr_lds = lds + OFF_KR;
;   float* ws = (float*)(lds + OFF_WS) + wid * 64; float* li_l = ws; float* al_l = ws + 32;
;   char* Qr_l = lds + OFF_QR + wid * 4096;
;   const float* btab = (const float*)(lds + OFF_BT);
;   float m_reg = -1e30f, l_reg = 0; f32x16 o[4] = {}; bf16x8 qr[8] = {}; i32x8 q8[3] = {};
;   if constexpr (MODE != 0) {
;     const bf16_t* Qw = Qb + (long)(wid * QBLK + r32) * LDQ + hi * 8;
; #pragma unroll
;     for (int d0 = 0; d0 < 8; ++d0) qr[d0] = ld8(Qw + d0 * 16);
;   } else {
;     const bf16_t* Qrow = Qb + (long)(wid * QBLK + r32) * LDQ;
;     ...
; #pragma unroll
;     for (int kb = 0; kb < 2; ++kb) { unsigned w[8];
; #pragma unroll
;       for (int c = 0; c < 4; ++c) { const bf16x8 x = ld8(Qrow + kb * 64 + hi * 32 + c * 8);
;         w[2 * c] = pk4_fp8(BF2F(x[0]), BF2F(x[1]), BF2F(x[2]), BF2F(x[3])); w[2 * c + 1] = pk4_fp8(BF2F(x[4]), BF2F(x[5]), BF2F(x[6]), BF2F(x[7])); }
;       q8[kb] = (i32x8){(int)w[0], (int)w[1], (int)w[2], (int)w[3], (int)w[4], (int)w[5], (int)w[6], (int)w[7]}; }
;     { const f32x2* csr = cs + (long)(wid * QBLK + r32) * 32; unsigned w[8];
; #pragma unroll
;       for (int c = 0; c < 4; ++c) { const bf16x8 x1 = ld8(Qrow + 128 + c * 8), x2 = ld8(Qrow + 160 + c * 8); float r[8];
; #pragma unroll
;         for (int e = 0; e < 8; ++e) { const f32x2 t = csr[c * 8 + e]; const float a = BF2F(x1[e]), b = BF2F(x2[e]); r[e] = hi ? (b * t.x + a * t.y) : (a * t.x - b * t.y); }
;         w[2 * c] = pk4_fp8(r[0], r[1], r[2], r[3]); w[2 * c + 1] = pk4_fp8(r[4], r[5], r[6], r[7]); }
;       q8[2] = (i32x8){(int)w[0], (int)w[1], (int)w[2], (int)w[3], (int)w[4], (int)w[5], (int)w[6], (int)w[7]}; }
;     ...
;   }
;   const int sr = tid >> 4, sc = (tid & 15) * 8, vst0 = v_st(sr, sc), vst1 = v_st(32 + sr, sc);
;   const int krr = tid >> 3, krc = (tid & 7) * 8;
;   const int kr0 = tid / 12, kc0 = tid - kr0 * 12, kr1 = (512 + tid) / 12, kc1 = (512 + tid) - kr1 * 12;
;     ...
;   const int ks0r = KAPPA(kr0), ks1r = KAPPA(kr1), vd = tid >> 2, vch = tid & 3;
;   const int vb0 = (int)(uintptr_t)V_lds + v_rd_base(lane);
;   struct { bf16x8 vs0, vs1, ks0, ks1; } sr_[SD];
.LBB0_624:
	s_or_b64 exec, exec, s[8:9]
	v_mov_b32_e32 v146, v190
	s_nop 0
	v_ashrrev_i32_e32 v0, 6, v146
	v_cmp_lt_i32_e32 vcc, 3, v0
	s_and_saveexec_b64 s[8:9], vcc
	s_setprio 1
	s_or_b64 exec, exec, s[8:9]
	v_lshlrev_b32_e32 v4, 8, v2
	v_ashrrev_i32_e32 v115, 31, v114
	v_ashrrev_i32_e32 v5, 31, v4
	v_lshl_add_u64 v[196:197], v[4:5], 0, v[114:115]
	v_mov_b64_e32 v[4:5], s[70:71]
	v_mad_u64_u32 v[4:5], s[8:9], v196, s56, v[4:5]
	s_movk_i32 s8, 0xc0
	s_nop 0
	v_mul_lo_u32 v6, v192, s8
	v_mad_i32_i24 v5, v197, s56, v5
	v_ashrrev_i32_e32 v7, 31, v6
	v_lshl_add_u64 v[4:5], v[6:7], 1, v[4:5]
	v_ashrrev_i32_e32 v145, 14, v114
	v_mov_b64_e32 v[6:7], s[76:77]
	v_mad_i64_i32 v[6:7], s[8:9], v145, s1, v[6:7]
	v_lshlrev_b32_e32 v3, 7, v147
	v_and_b32_e32 v223, 31, v146
	v_lshlrev_b32_e32 v194, 5, v0
	v_mad_i64_i32 v[132:133], s[8:9], v3, v192, v[6:7]
	v_ashrrev_i32_e32 v3, 31, v2
	v_or_b32_e32 v6, v194, v223
	v_lshlrev_b64 v[2:3], 16, v[2:3]
	v_and_b32_e32 v144, 32, v146
	v_ashrrev_i32_e32 v7, 31, v6
	v_lshl_add_u64 v[2:3], s[86:87], 0, v[2:3]
	v_mad_i64_i32 v[4:5], s[8:9], v6, s56, v[4:5]
	v_lshlrev_b32_e32 v0, 1, v144
	v_lshlrev_b64 v[6:7], 8, v[6:7]
	v_lshl_add_u64 v[8:9], v[4:5], 0, v[0:1]
	v_lshl_add_u64 v[6:7], v[2:3], 0, v[6:7]
	global_load_dwordx4 v[128:131], v[8:9], off
	global_load_dwordx4 v[116:119], v[8:9], off offset:16
	global_load_dwordx4 v[124:127], v[8:9], off offset:32
	global_load_dwordx4 v[120:123], v[8:9], off offset:48
	global_load_dwordx4 v[110:113], v[8:9], off offset:128
	global_load_dwordx4 v[106:109], v[8:9], off offset:144
	global_load_dwordx4 v[102:105], v[8:9], off offset:160
	global_load_dwordx4 v[98:101], v[8:9], off offset:176
	global_load_dwordx4 v[74:77], v[6:7], off offset:48
	global_load_dwordx4 v[86:89], v[6:7], off offset:32
	global_load_dwordx4 v[90:93], v[6:7], off offset:16
	global_load_dwordx4 v[94:97], v[6:7], off
	global_load_dwordx4 v[78:81], v[4:5], off offset:256
	global_load_dwordx4 v[54:57], v[4:5], off offset:272
	global_load_dwordx4 v[82:85], v[4:5], off offset:320
	global_load_dwordx4 v[58:61], v[4:5], off offset:336
	global_load_dwordx4 v[50:53], v[6:7], off offset:112
	global_load_dwordx4 v[62:65], v[6:7], off offset:96
	global_load_dwordx4 v[66:69], v[6:7], off offset:80
	global_load_dwordx4 v[70:73], v[6:7], off offset:64
	global_load_dwordx4 v[10:13], v[6:7], off offset:176
	global_load_dwordx4 v[22:25], v[6:7], off offset:160
	global_load_dwordx4 v[26:29], v[6:7], off offset:144
	global_load_dwordx4 v[30:33], v[6:7], off offset:128
	global_load_dwordx4 v[14:17], v[4:5], off offset:288
	global_load_dwordx4 v[38:41], v[4:5], off offset:304
	global_load_dwordx4 v[18:21], v[4:5], off offset:352
	global_load_dwordx4 v[42:45], v[4:5], off offset:368
	global_load_dwordx4 v[34:37], v[6:7], off offset:240
	global_load_dwordx4 v[46:49], v[6:7], off offset:224
	s_nop 0
	global_load_dwordx4 v[2:5], v[6:7], off offset:208
	s_nop 0
	global_load_dwordx4 v[6:9], v[6:7], off offset:192
	v_ashrrev_i32_e32 v148, 2, v146
	v_lshlrev_b32_e32 v0, 7, v148
	v_lshl_add_u64 v[132:133], v[132:133], 0, v[0:1]
	v_lshlrev_b32_e32 v0, 4, v146
	v_and_b32_e32 v0, 48, v0
	v_lshl_add_u64 v[168:169], v[132:133], 0, v[0:1]
	global_load_dwordx4 v[132:135], v[168:169], off
	v_lshlrev_b64 v[136:137], 6, v[114:115]
	v_mul_hi_i32 v115, v146, s7
	v_lshl_add_u64 v[150:151], s[82:83], 0, v[136:137]
	v_lshrrev_b32_e32 v136, 31, v115
	v_ashrrev_i32_e32 v115, 1, v115
	v_add_u32_e32 v115, v115, v136
	v_mad_u64_u32 v[136:137], s[8:9], v115, -12, v[146:147]
	v_lshlrev_b32_e32 v137, 3, v115
	v_and_b32_e32 v170, 32, v137
	v_lshrrev_b32_e32 v137, 1, v115
	v_and_b32_e32 v171, 16, v137
	v_and_b32_e32 v172, 3, v115
	v_and_b32_e32 v173, 12, v137
	v_or_b32_e32 v137, v171, v172
	v_or3_b32 v195, v137, v170, v173
	v_cmp_lt_i32_e64 s[10:11], 7, v136
	v_lshlrev_b32_e32 v152, 4, v136
	v_lshlrev_b32_e32 v164, 6, v195
	s_and_saveexec_b64 s[8:9], s[10:11]
	s_xor_b64 s[8:9], exec, s[8:9]
	v_mov_b32_e32 v165, v1
	v_lshl_add_u64 v[136:137], v[150:151], 0, v[164:165]
	v_add_u32_e32 v138, 0xffffff80, v152
	v_mov_b32_e32 v139, v1
	v_lshl_add_u64 v[136:137], v[136:137], 0, v[138:139]
	s_or_saveexec_b64 s[8:9], s[8:9]
	v_mov_b64_e32 v[138:139], s[74:75]
	v_lshlrev_b32_e32 v198, 9, v192
	v_mad_i64_i32 v[138:139], s[12:13], v114, s0, v[138:139]
	v_ashrrev_i32_e32 v199, 31, v198
	v_lshl_add_u64 v[162:163], v[138:139], 0, v[198:199]
	v_mul_u32_u24_e32 v166, 0xc00, v195
	v_ashrrev_i32_e32 v153, 31, v152
	s_xor_b64 exec, exec, s[8:9]
	v_mov_b32_e32 v167, v1
	v_lshl_add_u64 v[136:137], v[162:163], 0, v[166:167]
	v_lshl_add_u64 v[136:137], v[136:137], 0, v[152:153]
	s_or_b64 exec, exec, s[8:9]
	global_load_dwordx4 v[136:139], v[136:137], off
	v_add_u32_e32 v140, 0x200, v146
	v_mul_hi_i32 v141, v140, s7
	v_lshrrev_b32_e32 v142, 31, v141
	v_ashrrev_i32_e32 v141, 1, v141
	v_add_u32_e32 v155, v141, v142
	v_mad_u64_u32 v[156:157], s[8:9], v155, -12, v[140:141]
	v_lshlrev_b32_e32 v140, 3, v155
	v_and_b32_e32 v157, 32, v140
	v_lshrrev_b32_e32 v140, 1, v155
	v_and_b32_e32 v174, 16, v140
	v_and_b32_e32 v175, 3, v155
	s_movk_i32 s8, 0xff
	v_and_b32_e32 v176, 12, v140
	v_or_b32_e32 v140, v174, v175
	v_cmp_lt_i32_e32 vcc, s8, v146
	s_movk_i32 s8, 0x100
	v_or3_b32 v224, v140, v157, v176
	v_cmp_gt_i32_e64 s[12:13], s8, v146
	v_lshlrev_b32_e32 v154, 4, v156
	s_and_saveexec_b64 s[14:15], s[12:13]
	s_cbranch_execz .LBB0_636
	v_cmp_lt_i32_e64 s[8:9], 7, v156
	v_lshlrev_b32_e32 v140, 4, v156
	s_and_saveexec_b64 s[16:17], s[8:9]
	s_xor_b64 s[8:9], exec, s[16:17]
	v_lshlrev_b32_e32 v142, 6, v224
	v_mov_b32_e32 v143, v1
	v_lshl_add_u64 v[142:143], v[150:151], 0, v[142:143]
	v_add_u32_e32 v140, 0xffffff80, v140
	v_mov_b32_e32 v141, v1
	v_lshl_add_u64 v[142:143], v[142:143], 0, v[140:141]
	s_andn2_saveexec_b64 s[8:9], s[8:9]
	v_mul_u32_u24_e32 v142, 0xc00, v224
	v_mov_b32_e32 v143, v1
	v_lshl_add_u64 v[142:143], v[162:163], 0, v[142:143]
	v_ashrrev_i32_e32 v141, 31, v140
	v_lshl_add_u64 v[142:143], v[142:143], 0, v[140:141]
	s_or_b64 exec, exec, s[8:9]
	global_load_dwordx4 v[178:181], v[142:143], off

; #define SWAIT() do { if constexpr (SD == 1) asm volatile("s_waitcnt vmcnt(0)" ::: "memory"); else if constexpr (MODE == 0) asm volatile("s_waitcnt vmcnt(5)" ::: "memory"); else asm volatile("s_waitcnt vmcnt(4)" ::: "memory"); } while (0)
; template <int MODE>
; __device__ __forceinline__ void partialSM(f32x16& p0, f32x16& p1, float& m_reg, float& mn, float& alpha, const float C, int kb, const float* btab, const bool nomask) {
;     ...
;     { const bool keep = __all((pmax - m_reg) * C <= (MODE == 0 ? 7.5f : 11.5f)); mn = keep ? m_reg : fmaxf(m_reg, pmax);   alpha = __builtin_amdgcn_exp2f((m_reg - mn) * C); m_reg = mn; }
;     const float mnC = -mn * C;
; #pragma unroll
;     for (int r = 0; r < 16; ++r) p0[r] = fmaf(p0[r], C, mnC);
; #pragma unroll
;     for (int r = 0; r < 16; ++r) p1[r] = fmaf(p1[r], C, mnC);
; #pragma unroll
;     for (int r = 0; r < 16; ++r) p0[r] = __builtin_amdgcn_exp2f(p0[r]);
; template <int MODE, int SD> ...
;     ...
;   SLOAD(SE, 0); asm volatile("s_waitcnt vmcnt(0)" ::: "memory"); SWRITE(0, SE); __syncthreads();
;   qkt<MODE>(pA0, pA1, K_lds, Kr_lds, Qr_l, qr, q8, r32, hi); partialSM<MODE>(pA0, pA1, m_reg, mnA, alA, C, kbl, btab, nomask);
;   SLOAD(SO, KVBLK); if constexpr (SD == 2) { if (2 < NT) SLOAD(SE, 2 * KVBLK); }
;   SWAIT(); SWRITE(1, SO); __syncthreads();
;   for (int j = 1; j + 1 < NT; j += 2) {
.LBB0_648:
	s_or_b64 exec, exec, s[20:21]
	v_max_f32_e32 v42, 0xf149f2ca, v46
	v_cndmask_b32_e64 v237, v222, v42, s[14:15]
	v_mul_f32_e32 v42, 0xbdd53b94, v237
	v_fmamk_f32 v18, v18, 0x3dd53b94, v42
	v_fmamk_f32 v19, v19, 0x3dd53b94, v42
	v_fmamk_f32 v20, v20, 0x3dd53b94, v42
	v_fmamk_f32 v21, v21, 0x3dd53b94, v42
	v_fmamk_f32 v22, v22, 0x3dd53b94, v42
	v_fmamk_f32 v23, v23, 0x3dd53b94, v42
	v_fmamk_f32 v24, v24, 0x3dd53b94, v42
	v_fmamk_f32 v25, v25, 0x3dd53b94, v42
	v_fmamk_f32 v26, v26, 0x3dd53b94, v42
	v_fmamk_f32 v27, v27, 0x3dd53b94, v42
	v_fmamk_f32 v28, v28, 0x3dd53b94, v42
	v_fmamk_f32 v29, v29, 0x3dd53b94, v42
	v_fmamk_f32 v30, v30, 0x3dd53b94, v42
	v_fmamk_f32 v31, v31, 0x3dd53b94, v42
	v_fmamk_f32 v32, v32, 0x3dd53b94, v42
	v_fmamk_f32 v33, v33, 0x3dd53b94, v42
	v_exp_f32_e32 v66, v18
	v_exp_f32_e32 v67, v19
	v_exp_f32_e32 v68, v20
	v_exp_f32_e32 v69, v21
	v_exp_f32_e32 v70, v22
	v_exp_f32_e32 v71, v23
	v_exp_f32_e32 v72, v24
	v_exp_f32_e32 v73, v25
	v_exp_f32_e32 v74, v26
	v_exp_f32_e32 v75, v27
	v_exp_f32_e32 v76, v28
	v_exp_f32_e32 v77, v29
	v_exp_f32_e32 v78, v30
	v_exp_f32_e32 v79, v31
	v_exp_f32_e32 v80, v32
	v_exp_f32_e32 v81, v33
	s_waitcnt vmcnt(0)
	v_mul_u32_u24_e32 v18, 0xd0, v223
	s_waitcnt vmcnt(1)
	ds_write_b128 v225, v[34:37] offset:16384
	s_waitcnt vmcnt(0)
	ds_write_b128 v226, v[38:41] offset:49152
	s_and_saveexec_b64 s[14:15], vcc
	s_xor_b64 s[14:15], exec, s[14:15]
	v_lshlrev_b32_e32 v154, 4, v156
	v_mul_lo_u32 v177, v155, s90
	s_andn2_saveexec_b64 s[14:15], s[14:15]
	v_add3_u32 v19, 0, v177, v154
	ds_write_b128 v19, v[178:181] offset:49152
	s_or_b64 exec, exec, s[14:15]
	v_pk_fma_f32 v[98:99], v[2:3], s[78:79], v[42:43] op_sel_hi:[1,0,0]
	v_and_b32_e32 v2, 0x3fffffc0, v146
	v_pk_fma_f32 v[100:101], v[4:5], s[78:79], v[42:43] op_sel_hi:[1,0,0]
	v_lshl_add_u32 v4, v2, 2, s91
	v_lshrrev_b32_e32 v2, 3, v146
	v_and_b32_e32 v227, 4, v2
	v_mov_b32_e32 v2, v152
	v_mov_b32_e32 v3, v1
	v_lshl_add_u64 v[200:201], v[150:151], 0, v[2:3]
	v_add_u32_e32 v2, 0xffffff80, v154
	v_lshl_add_u64 v[202:203], v[150:151], 0, v[2:3]
	v_ashrrev_i32_e32 v155, 31, v154
	v_add_u32_e32 v2, v157, v174
	v_pk_fma_f32 v[106:107], v[10:11], s[78:79], v[42:43] op_sel_hi:[1,0,0]
	v_add3_u32 v10, v2, v176, v175
	v_lshl_add_u64 v[2:3], v[160:161], 0, v[154:155]
	v_lshl_add_u32 v229, v223, 2, v4
	v_lshl_add_u32 v228, v227, 2, v4
	v_mad_u64_u32 v[4:5], s[16:17], v10, s0, v[2:3]
	v_lshl_add_u64 v[204:205], s[84:85], 0, v[4:5]
	v_add_u32_e32 v4, v170, v171
	v_add3_u32 v11, v4, v173, v172
	v_lshl_add_u64 v[4:5], v[160:161], 0, v[152:153]
	v_pk_fma_f32 v[102:103], v[6:7], s[78:79], v[42:43] op_sel_hi:[1,0,0]
	v_mad_u64_u32 v[6:7], s[16:17], v11, s0, v[4:5]
	v_lshl_add_u64 v[206:207], s[84:85], 0, v[6:7]
	v_mad_u64_u32 v[6:7], s[16:17], v192, v147, v[148:149]
	v_lshlrev_b64 v[6:7], 7, v[6:7]
	v_pk_fma_f32 v[104:105], v[8:9], s[78:79], v[42:43] op_sel_hi:[1,0,0]
	v_lshl_add_u64 v[8:9], v[6:7], 0, v[158:159]
	s_nop 0
	v_lshl_add_u64 v[6:7], v[8:9], 0, v[0:1]
	v_add_u32_e32 v0, 0xc0, v10
	v_mul_u32_u24_e32 v0, 0xc00, v0
	v_sub_f32_e32 v19, 0xf149f2ca, v237
	v_lshl_add_u64 v[2:3], v[2:3], 0, v[0:1]
	v_add_u32_e32 v0, 0xc0, v11
	v_mul_f32_e32 v19, 0x3dd53b94, v19
	v_readlane_b32 s16, v255, 19
	v_mul_u32_u24_e32 v0, 0xc00, v0
	v_exp_f32_e32 v232, v19
	v_pk_fma_f32 v[112:113], v[16:17], s[78:79], v[42:43] op_sel_hi:[1,0,0]
	v_pk_fma_f32 v[110:111], v[14:15], s[78:79], v[42:43] op_sel_hi:[1,0,0]
	v_mul_u32_u24_e32 v16, 0x50, v223
	v_readlane_b32 s17, v255, 20
	v_lshl_add_u64 v[210:211], s[74:75], 0, v[2:3]
	v_lshl_add_u64 v[2:3], v[4:5], 0, v[0:1]
	v_mov_b32_e32 v14, v1
	v_mov_b32_e32 v15, v1
	v_pk_fma_f32 v[108:109], v[12:13], s[78:79], v[42:43] op_sel_hi:[1,0,0]
	v_add_u32_e32 v17, 0, v177
	v_lshl_add_u64 v[208:209], s[16:17], 0, v[6:7]
	v_lshl_add_u64 v[212:213], s[74:75], 0, v[2:3]
	v_mov_b32_e32 v0, v1
	v_mov_b32_e32 v2, v1
	v_mov_b32_e32 v3, v1
	v_mov_b32_e32 v4, v1
	v_mov_b32_e32 v5, v1
	v_mov_b32_e32 v6, v1
	v_mov_b32_e32 v7, v1
	v_mov_b32_e32 v8, v1
	v_mov_b32_e32 v9, v1
	v_mov_b32_e32 v10, v1
	v_mov_b32_e32 v11, v1
	v_mov_b32_e32 v12, v1
	v_mov_b32_e32 v13, v1
	v_add_u32_e32 v231, v50, v18
	v_add_u32_e32 v230, v50, v16
	v_mov_b64_e32 v[64:65], v[14:15]
	v_mov_b64_e32 v[48:49], v[14:15]
	v_mov_b64_e32 v[32:33], v[14:15]
	v_add_u32_e32 v234, v17, v154
	v_mov_b64_e32 v[62:63], v[12:13]
	v_mov_b64_e32 v[60:61], v[10:11]
	v_mov_b64_e32 v[58:59], v[8:9]
	v_mov_b64_e32 v[56:57], v[6:7]
	v_mov_b64_e32 v[54:55], v[4:5]
	v_mov_b64_e32 v[52:53], v[2:3]
	v_mov_b64_e32 v[50:51], v[0:1]
	v_mov_b64_e32 v[46:47], v[12:13]
	v_mov_b64_e32 v[44:45], v[10:11]
	v_mov_b64_e32 v[42:43], v[8:9]
	v_mov_b64_e32 v[40:41], v[6:7]
	v_mov_b64_e32 v[38:39], v[4:5]
	v_mov_b64_e32 v[36:37], v[2:3]
	v_mov_b64_e32 v[34:35], v[0:1]
	v_mov_b64_e32 v[30:31], v[12:13]
	v_mov_b64_e32 v[28:29], v[10:11]
	v_mov_b64_e32 v[26:27], v[8:9]
	v_mov_b64_e32 v[24:25], v[6:7]
	v_mov_b64_e32 v[22:23], v[4:5]
	v_mov_b64_e32 v[20:21], v[2:3]
	v_mov_b64_e32 v[18:19], v[0:1]
	v_mov_b64_e32 v[16:17], v[14:15]
	s_mov_b32 s24, 2
	v_lshrrev_b32_e32 v233, 6, v147
	v_cmp_lt_i32_e64 s[14:15], 7, v156
	v_mov_b32_e32 v193, 0
	s_mov_b32 s25, 1
	s_mov_b64 s[16:17], 0
	v_mov_b64_e32 v[14:15], v[12:13]
	v_mov_b64_e32 v[12:13], v[10:11]
	v_mov_b64_e32 v[10:11], v[8:9]
	v_mov_b64_e32 v[8:9], v[6:7]
	v_mov_b64_e32 v[6:7], v[4:5]
	v_mov_b64_e32 v[4:5], v[2:3]
	v_mov_b64_e32 v[2:3], v[0:1]
	s_waitcnt lgkmcnt(0)
	s_barrier
	s_branch .LBB0_655

; #define SBAR() __builtin_amdgcn_sched_barrier(0)
; #define PVC(voff) do { if constexpr (MODE == 0) pv8(o, V_lds + (voff), pa0, pa1, r32, hi); else pv_d0(o, vb0 + (voff), pa0, pa1, pa2, pa3); } while (0)
; #define FSM(P0, P1, AL) do { if constexpr (MODE == 0) finishSM8(P0, P1, AL, l_reg, pa0, pa1); else finishSM(P0, P1, AL, l_reg, pa0, pa1, pa2, pa3); } while (0)
; #define SG_QKT() do { if (SGQ) { __builtin_amdgcn_sched_group_barrier(0x100, SGQ_PRE, 0); if constexpr (MODE == 0) { _Pragma("unroll") for (int _g = 0; _g < 6; ++_g) SG_ONE(2, 12, 3); } else { _Pragma("unroll") for (int _g = 0; _g < 16; ++_g) SG_ONE(1, 5, 1); } } } while (0)
; #define SG_PV() do { if (SGP) { __builtin_amdgcn_sched_group_barrier(0x100, SGP_PRE, 0); if constexpr (MODE == 0) { _Pragma("unroll") for (int _g = 0; _g < 4; ++_g) SG_ONE(2, 24, 4); } else { _Pragma("unroll") for (int _g = 0; _g < 16; ++_g) SG_ONE(2, 6, 1); } } } while (0)
; __device__ __forceinline__ void finishSM8(f32x16& p0, f32x16& p1, float alpha, float& l_reg, bf16x8& pa0, bf16x8& pa1) {
; #pragma unroll
;   for (int r = 0; r < 16; ++r) p1[r] = __builtin_amdgcn_exp2f(p1[r]);
;   float ps = 0;
; #pragma unroll
;   for (int r = 0; r < 16; ++r) ps += p0[r];
; #pragma unroll
;   for (int r = 0; r < 16; ++r) ps += p1[r];
;   { auto rr = __builtin_amdgcn_permlane32_swap(__float_as_uint(ps), __float_as_uint(ps), false, false); ps = __uint_as_float(rr[0]) + __uint_as_float(rr[1]); }
;   l_reg = l_reg * alpha + ps;
; template <int MODE, int SD> ...
;     ...
;   for (int j = 1; j + 1 < NT; j += 2) {
;     SBAR(); qkt<MODE>(pB0, pB1, K_lds + SHM_K, Kr_lds + SHM_KR, Qr_l, qr, q8, r32, hi);
;     FSM(pA0, pA1, alA); SG_QKT(); SBAR();
;     SLOAD(SO, (j + SD) * KVBLK); SBAR();
;     PVC(0); partialSM<MODE>(pB0, pB1, m_reg, mnB, alB, C, kbl + j * KVBLK, btab, nomask); asm volatile("" : "+v"(pB0), "+v"(pB1), "+v"(alB)); SG_PV(); SBAR();
.LBB0_654:
	v_add_f32_e32 v82, v235, v236
	s_add_i32 s24, s24, 2
	v_fmac_f32_e32 v82, v232, v193
	v_add_f32_e32 v193, v239, v240
	s_add_i32 s25, s25, 2
	s_mov_b64 s[20:21], 0x4000
	v_cmp_ge_u32_e32 vcc, s24, v233
	v_fmac_f32_e32 v193, v82, v0
	v_lshl_add_u64 v[204:205], v[204:205], 0, s[94:95]
	v_lshl_add_u64 v[206:207], v[206:207], 0, s[94:95]
	v_lshl_add_u64 v[208:209], v[208:209], 0, s[20:21]
	v_lshl_add_u64 v[210:211], v[210:211], 0, s[94:95]
	v_lshl_add_u64 v[212:213], v[212:213], 0, s[94:95]
	s_or_b64 s[16:17], vcc, s[16:17]
	v_mov_b32_e32 v232, v170
	s_waitcnt lgkmcnt(0)
	s_barrier
	s_andn2_b64 exec, exec, s[16:17]
	s_cbranch_execz .LBB0_686
.LBB0_655:
	ds_read_b128 v[82:85], v231 offset:49152
	ds_read_b128 v[86:89], v231 offset:49168
	ds_read_b128 v[122:125], v231 offset:49216
	ds_read_b128 v[126:129], v231 offset:49232
	ds_read_b128 v[162:165], v231 offset:49280
	ds_read_b128 v[166:169], v231 offset:49296
	ds_read_b128 v[146:149], v231 offset:55808
	ds_read_b128 v[150:153], v231 offset:55824
	ds_read_b128 v[154:157], v231 offset:55872
	ds_read_b128 v[158:161], v231 offset:55888
	ds_read_b128 v[170:173], v231 offset:55936
	ds_read_b128 v[174:177], v231 offset:55952
	global_load_dwordx4 v[182:185], v[208:209], off
	s_lshl_b32 s26, s24, 6
	s_and_saveexec_b64 s[20:21], s[10:11]
	s_xor_b64 s[20:21], exec, s[20:21]
	s_cbranch_execz .LBB0_658
	v_or_b32_e32 v0, s26, v195
	v_lshlrev_b64 v[90:91], 6, v[0:1]
	v_lshl_add_u64 v[90:91], v[200:201], 0, v[90:91]
	v_lshl_add_u64 v[90:91], v[90:91], 0, s[92:93]
	s_andn2_saveexec_b64 s[20:21], s[20:21]
	s_cbranch_execnz .LBB0_659

; template <int MODE>
; __device__ __forceinline__ void partialSM(f32x16& p0, f32x16& p1, float& m_reg, float& mn, float& alpha, const float C, int kb, const float* btab, const bool nomask) {
;     ...
;     float pmax = p0[0];
; #pragma unroll
;     for (int r = 1; r < 16; ++r) pmax = fmaxf(pmax, p0[r]);
; #pragma unroll
;     for (int r = 0; r < 16; ++r) pmax = fmaxf(pmax, p1[r]);
;     { auto rr = __builtin_amdgcn_permlane32_swap(__float_as_uint(pmax), __float_as_uint(pmax), false, false); pmax = fmaxf(__uint_as_float(rr[0]), __uint_as_float(rr[1])); }
;     { const bool keep = __all((pmax - m_reg) * C <= (MODE == 0 ? 7.5f : 11.5f)); mn = keep ? m_reg : fmaxf(m_reg, pmax);   alpha = __builtin_amdgcn_exp2f((m_reg - mn) * C); m_reg = mn; }
;     const float mnC = -mn * C;
; #pragma unroll
;     for (int r = 0; r < 16; ++r) p0[r] = fmaf(p0[r], C, mnC);
; #pragma unroll
;     for (int r = 0; r < 16; ++r) p1[r] = fmaf(p1[r], C, mnC);
; #pragma unroll
;     for (int r = 0; r < 16; ++r) p0[r] = __builtin_amdgcn_exp2f(p0[r]);
;   }
; }
; __device__ __forceinline__ void finishSM(f32x16& p0, f32x16& p1, float alpha, float& l_reg, bf16x8& pa0, bf16x8& pa1, bf16x8& pa2, bf16x8& pa3) {
; #pragma unroll
;   for (int r = 0; r < 16; ++r) p1[r] = __builtin_amdgcn_exp2f(p1[r]);
;   float ps = 0;
; #pragma unroll
;   for (int r = 0; r < 16; ++r) ps += p0[r];
; #pragma unroll
;   for (int r = 0; r < 16; ++r) ps += p1[r];
;   { auto rr = __builtin_amdgcn_permlane32_swap(__float_as_uint(ps), __float_as_uint(ps), false, false); ps = __uint_as_float(rr[0]) + __uint_as_float(rr[1]); }
;   l_reg = l_reg * alpha + ps;
;     ...
;   PK4(p0, 0, pa0); PK4(p0, 8, pa1); PK4(p1, 0, pa2); PK4(p1, 8, pa3);
;     ...
; }
; template <int MODE>
; __device__ __forceinline__ void qkt(f32x16& p0, f32x16& p1, const char* Ks, const char* Krs, const char* Qrs, const bf16x8* qr, const i32x8* q8, int r32, int hi) {
;   p0 = f32x16{}; p1 = f32x16{};
;   if constexpr (MODE == 0) {
; #pragma unroll
;     for (int kb = 0; kb < 3; ++kb) {
; #pragma unroll
;       for (int hf = 0; hf < 2; ++hf) { const char* a_ = Ks + (hf * 32 + r32) * 208 + kb * 64 + hi * 32;
;         const u32x4 lo = *reinterpret_cast<const u32x4*>(a_), h4 = *reinterpret_cast<const u32x4*>(a_ + 16);
;         const i32x8 a = {(int)lo.x, (int)lo.y, (int)lo.z, (int)lo.w, (int)h4.x, (int)h4.y, (int)h4.z, (int)h4.w};
.LBB0_665:
	s_or_b64 exec, exec, s[20:21]
	s_waitcnt lgkmcnt(10)
	v_mfma_scale_f32_32x32x64_f8f6f4 v[82:97], v[82:89], v[114:121], 0, v216, v216 op_sel_hi:[0,0,0]
	v_exp_f32_e32 v240, v98
	v_exp_f32_e32 v242, v99
	v_exp_f32_e32 v239, v100
	v_exp_f32_e32 v241, v101
	v_exp_f32_e32 v245, v102
	v_exp_f32_e32 v246, v103
	v_add_f32_e32 v0, 0, v66
	v_add_f32_e32 v0, v67, v0
	s_waitcnt lgkmcnt(8)
	v_mfma_scale_f32_32x32x64_f8f6f4 v[82:97], v[122:129], v[130:137], v[82:97], v216, v216 op_sel_hi:[0,0,0]
	v_exp_f32_e32 v243, v104
	v_exp_f32_e32 v244, v105
	v_exp_f32_e32 v247, v106
	v_exp_f32_e32 v250, v107
	v_exp_f32_e32 v248, v108
	v_exp_f32_e32 v249, v109
	v_add_f32_e32 v0, v68, v0
	v_add_f32_e32 v0, v69, v0
	s_waitcnt lgkmcnt(6)
	v_mfma_scale_f32_32x32x64_f8f6f4 v[82:97], v[162:169], v[138:145], v[82:97], v216, v216 op_sel_hi:[0,0,0]
	v_exp_f32_e32 v191, v110
	v_exp_f32_e32 v217, v111
	v_exp_f32_e32 v251, v112
	v_exp_f32_e32 v252, v113
	v_add_f32_e32 v0, v70, v0
	v_add_f32_e32 v0, v71, v0
	v_add_f32_e32 v0, v72, v0
	v_add_f32_e32 v0, v73, v0
	v_add_f32_e32 v0, v74, v0
	v_add_f32_e32 v0, v75, v0
	s_waitcnt lgkmcnt(4)
	v_mfma_scale_f32_32x32x64_f8f6f4 v[98:113], v[146:153], v[114:121], 0, v216, v216 op_sel_hi:[0,0,0]
	v_add_f32_e32 v0, v76, v0
	v_add_f32_e32 v0, v77, v0
	v_add_f32_e32 v0, v78, v0
	v_add_f32_e32 v0, v79, v0
	v_add_f32_e32 v0, v80, v0
	v_add_f32_e32 v0, v81, v0
	v_add_f32_e32 v0, v240, v0
	v_add_f32_e32 v0, v242, v0
	v_add_f32_e32 v0, v239, v0
	v_add_f32_e32 v0, v241, v0
	v_add_f32_e32 v0, v245, v0
	s_waitcnt lgkmcnt(2)
	v_mfma_scale_f32_32x32x64_f8f6f4 v[98:113], v[154:161], v[130:137], v[98:113], v216, v216 op_sel_hi:[0,0,0]
	v_add_f32_e32 v0, v246, v0
	v_add_f32_e32 v0, v243, v0
	v_add_f32_e32 v0, v244, v0
	v_add_f32_e32 v0, v247, v0
	v_add_f32_e32 v0, v250, v0
	v_add_f32_e32 v0, v248, v0
	v_add_f32_e32 v0, v249, v0
	v_add_f32_e32 v0, v191, v0
	v_add_f32_e32 v0, v217, v0
	v_add_f32_e32 v0, v251, v0
	s_waitcnt lgkmcnt(0)
	v_mfma_scale_f32_32x32x64_f8f6f4 v[98:113], v[170:177], v[138:145], v[98:113], v216, v216 op_sel_hi:[0,0,0]
	s_nop 0
	v_add_f32_e32 v235, v252, v0
	v_mov_b32_e32 v236, v235
	s_nop 1
	v_permlane32_swap_b32_e32 v235, v236
	ds_read_b128 v[154:157], v230
	ds_read_b128 v[158:161], v230 offset:16
	ds_read_b128 v[146:149], v230 offset:2560
	ds_read_b128 v[150:153], v230 offset:2576
	ds_read_b128 v[122:125], v230 offset:5120
	ds_read_b128 v[126:129], v230 offset:5136
	ds_read_b128 v[166:169], v230 offset:7696
	s_nop 3
	v_max_f32_e32 v0, v83, v83
	v_max_f32_e32 v162, v82, v82
	v_max_f32_e32 v0, v162, v0
	v_max3_f32 v0, v0, v84, v85
	v_max3_f32 v0, v0, v86, v87
	v_max3_f32 v0, v0, v88, v89
	v_max3_f32 v0, v0, v90, v91
	v_max3_f32 v0, v0, v92, v93
	v_max3_f32 v0, v0, v94, v95
	v_max3_f32 v0, v0, v96, v97
	v_max3_f32 v0, v0, v98, v99
	v_max3_f32 v0, v0, v100, v101
	v_max3_f32 v0, v0, v102, v103
	v_max3_f32 v0, v0, v104, v105
	v_max3_f32 v0, v0, v106, v107
	v_max3_f32 v0, v0, v108, v109
	v_max3_f32 v0, v0, v110, v111
	v_max3_f32 v0, v0, v112, v113
	v_mov_b32_e32 v162, v0
	s_nop 1
	v_permlane32_swap_b32_e32 v0, v162
	v_max_f32_e32 v162, v162, v162
	v_max_f32_e32 v0, v0, v0
	v_max_f32_e32 v0, v0, v162
	v_sub_f32_e32 v162, v0, v237
	v_mul_f32_e32 v162, 0x3dd53b94, v162
	v_cmp_ge_f32_e32 vcc, s57, v162
	s_cmp_eq_u64 vcc, exec
	v_max_f32_e32 v162, v237, v237
	s_cselect_b64 vcc, -1, 0
	v_max_f32_e32 v0, v162, v0
	v_cndmask_b32_e32 v238, v0, v237, vcc
	v_sub_f32_e32 v0, v237, v238
	v_mul_f32_e32 v0, 0x3dd53b94, v0
	v_exp_f32_e32 v0, v0
	ds_read_b128 v[162:165], v230 offset:7680
	s_waitcnt lgkmcnt(0)
	s_barrier
; __device__ __forceinline__ unsigned pk4_fp8(float a, float b, float c, float d) { int p = __builtin_amdgcn_cvt_pk_fp8_f32(a, b, 0, false); p = __builtin_amdgcn_cvt_pk_fp8_f32(c, d, p, true); return (unsigned)p; }
; #define SBAR() __builtin_amdgcn_sched_barrier(0)
; __device__ __forceinline__ void finishSM8(f32x16& p0, f32x16& p1, float alpha, float& l_reg, bf16x8& pa0, bf16x8& pa1) {
;     ...
;   const u32x4 w0 = {pk4_fp8(p0[0], p0[1], p0[2], p0[3]), pk4_fp8(p0[4], p0[5], p0[6], p0[7]), pk4_fp8(p0[8], p0[9], p0[10], p0[11]), pk4_fp8(p0[12], p0[13], p0[14], p0[15])};
;   const u32x4 w1 = {pk4_fp8(p1[0], p1[1], p1[2], p1[3]), pk4_fp8(p1[4], p1[5], p1[6], p1[7]), pk4_fp8(p1[8], p1[9], p1[10], p1[11]), pk4_fp8(p1[12], p1[13], p1[14], p1[15])};
;   pa0 = __builtin_bit_cast(bf16x8, w0); pa1 = __builtin_bit_cast(bf16x8, w1);
; }
; __device__ __forceinline__ void pv8(f32x16* o, const char* Vs, bf16x8 pa0, bf16x8 pa1, int r32, int hi) {
;   const u32x4 a0 = __builtin_bit_cast(u32x4, pa0), a1 = __builtin_bit_cast(u32x4, pa1);
;   const i32x8 P = {(int)a0.x, (int)a0.y, (int)a0.z, (int)a0.w, (int)a1.x, (int)a1.y, (int)a1.z, (int)a1.w};
; #pragma unroll
;   for (int d0 = 0; d0 < 4; ++d0) { const char* b_ = Vs + (d0 * 32 + r32) * 80 + hi * 32;
;     const u32x4 lo = *reinterpret_cast<const u32x4*>(b_), h4 = *reinterpret_cast<const u32x4*>(b_ + 16);
;     const i32x8 V = {(int)lo.x, (int)lo.y, (int)lo.z, (int)lo.w, (int)h4.x, (int)h4.y, (int)h4.z, (int)h4.w};
;     o[d0] = __builtin_amdgcn_mfma_scale_f32_32x32x64_f8f6f4(P, V, o[d0], 0, 0, 0, 0x7F7F7F7F, 0, 0x7F7F7F7F); }
; template <int MODE, int SD> ...
;     ...
;     PVC(0); partialSM<MODE>(pB0, pB1, m_reg, mnB, alB, C, kbl + j * KVBLK, btab, nomask); asm volatile("" : "+v"(pB0), "+v"(pB1), "+v"(alB)); SG_PV(); SBAR();
;     __syncthreads(); SWAIT(); SWRITE(0, SE);
;     RESC(alB); __syncthreads();
;     SBAR(); qkt<MODE>(pA0, pA1, K_lds, Kr_lds, Qr_l, qr, q8, r32, hi);
;     FSM(pB0, pB1, alB); SG_QKT(); SBAR();
;     if (SD == 1 || j + 3 < NT) SLOAD(SE, (j + 1 + SD) * KVBLK); SBAR();
;     PVC(SHM_V); partialSM<MODE>(pA0, pA1, m_reg, mnA, alA, C, kbl + (j + 1) * KVBLK, btab, nomask); asm volatile("" : "+v"(pA0), "+v"(pA1), "+v"(alA)); SG_PV(); SBAR();
;     __syncthreads(); SWAIT(); SWRITE(1, SO);
;     RESC(alA); __syncthreads();
	s_waitcnt vmcnt(0)
	s_waitcnt vmcnt(1)
	ds_write_b128 v225, v[182:185]
	s_waitcnt vmcnt(0)
	ds_write_b128 v226, v[186:189] offset:32768
	s_and_saveexec_b64 s[20:21], s[12:13]
	ds_write_b128 v234, v[178:181] offset:32768
	s_or_b64 exec, exec, s[20:21]
	v_mul_f32_e32 v182, 0xbdd53b94, v238
	v_mov_b32_e32 v170, 0
	v_mov_b32_e32 v171, 0
	v_mov_b32_e32 v172, 0
	v_mov_b32_e32 v173, 0
	v_mov_b32_e32 v174, 0
	v_mov_b32_e32 v175, 0
	v_mov_b32_e32 v176, 0
	v_mov_b32_e32 v177, 0
	v_cvt_pk_fp8_f32 v170, v66, v67
	v_cvt_pk_fp8_f32 v171, v70, v71
	v_cvt_pk_fp8_f32 v172, v74, v75
	v_cvt_pk_fp8_f32 v173, v78, v79
	v_cvt_pk_fp8_f32 v174, v240, v242
	v_cvt_pk_fp8_f32 v175, v245, v246
	v_cvt_pk_fp8_f32 v176, v247, v250
	v_cvt_pk_fp8_f32 v177, v191, v217
	v_cvt_pk_fp8_f32 v170, v68, v69 op_sel:[0,0,1]
	v_cvt_pk_fp8_f32 v171, v72, v73 op_sel:[0,0,1]
	v_cvt_pk_fp8_f32 v172, v76, v77 op_sel:[0,0,1]
	v_cvt_pk_fp8_f32 v173, v80, v81 op_sel:[0,0,1]
	v_cvt_pk_fp8_f32 v174, v239, v241 op_sel:[0,0,1]
	v_cvt_pk_fp8_f32 v175, v243, v244 op_sel:[0,0,1]
	v_cvt_pk_fp8_f32 v176, v248, v249 op_sel:[0,0,1]
	v_cvt_pk_fp8_f32 v177, v251, v252 op_sel:[0,0,1]
	v_cmp_gt_f32_e32 vcc, 1.0, v0
	s_nop 0
	v_mfma_scale_f32_32x32x64_f8f6f4 v[50:65], v[170:177], v[154:161], v[50:65], v216, v216 op_sel_hi:[0,0,0]
	v_fmamk_f32 v82, v82, 0x3dd53b94, v182
	v_exp_f32_e32 v82, v82
	v_fmamk_f32 v83, v83, 0x3dd53b94, v182
	v_exp_f32_e32 v83, v83
	v_fmamk_f32 v84, v84, 0x3dd53b94, v182
	v_exp_f32_e32 v84, v84
	v_fmamk_f32 v85, v85, 0x3dd53b94, v182
	v_exp_f32_e32 v85, v85
	v_mfma_scale_f32_32x32x64_f8f6f4 v[34:49], v[170:177], v[146:153], v[34:49], v216, v216 op_sel_hi:[0,0,0]
	v_fmamk_f32 v86, v86, 0x3dd53b94, v182
	v_exp_f32_e32 v86, v86
	v_fmamk_f32 v87, v87, 0x3dd53b94, v182
	v_exp_f32_e32 v87, v87
	v_fmamk_f32 v88, v88, 0x3dd53b94, v182
	v_exp_f32_e32 v88, v88
	v_fmamk_f32 v89, v89, 0x3dd53b94, v182
	v_exp_f32_e32 v89, v89
	v_mfma_scale_f32_32x32x64_f8f6f4 v[18:33], v[170:177], v[122:129], v[18:33], v216, v216 op_sel_hi:[0,0,0]
	v_fmamk_f32 v90, v90, 0x3dd53b94, v182
	v_exp_f32_e32 v90, v90
	v_fmamk_f32 v91, v91, 0x3dd53b94, v182
	v_exp_f32_e32 v91, v91
	v_fmamk_f32 v92, v92, 0x3dd53b94, v182
	v_exp_f32_e32 v92, v92
	v_fmamk_f32 v93, v93, 0x3dd53b94, v182
	v_exp_f32_e32 v93, v93
	v_mfma_scale_f32_32x32x64_f8f6f4 v[2:17], v[170:177], v[162:169], v[2:17], v216, v216 op_sel_hi:[0,0,0]
	v_fmamk_f32 v94, v94, 0x3dd53b94, v182
	v_exp_f32_e32 v94, v94
	v_fmamk_f32 v95, v95, 0x3dd53b94, v182
	v_exp_f32_e32 v95, v95
	v_fmamk_f32 v96, v96, 0x3dd53b94, v182
	v_exp_f32_e32 v96, v96
	v_fmamk_f32 v97, v97, 0x3dd53b94, v182
	v_exp_f32_e32 v97, v97
	v_pk_fma_f32 v[98:99], v[98:99], s[78:79], v[182:183] op_sel_hi:[1,0,0]
	v_pk_fma_f32 v[100:101], v[100:101], s[78:79], v[182:183] op_sel_hi:[1,0,0]
	v_pk_fma_f32 v[102:103], v[102:103], s[78:79], v[182:183] op_sel_hi:[1,0,0]
	v_pk_fma_f32 v[104:105], v[104:105], s[78:79], v[182:183] op_sel_hi:[1,0,0]
	v_pk_fma_f32 v[106:107], v[106:107], s[78:79], v[182:183] op_sel_hi:[1,0,0]
	v_pk_fma_f32 v[108:109], v[108:109], s[78:79], v[182:183] op_sel_hi:[1,0,0]
	v_pk_fma_f32 v[110:111], v[110:111], s[78:79], v[182:183] op_sel_hi:[1,0,0]
	v_pk_fma_f32 v[112:113], v[112:113], s[78:79], v[182:183] op_sel_hi:[1,0,0]
	s_cbranch_vccz .LBB0_671
	s_and_saveexec_b64 s[20:21], s[8:9]
	ds_write_b32 v229, v0 offset:128
	s_or_b64 exec, exec, s[20:21]
	s_waitcnt lgkmcnt(0)
	ds_read_b128 v[66:69], v228 offset:224
	ds_read_b128 v[70:73], v228 offset:192
	ds_read_b128 v[74:77], v228 offset:160
	ds_read_b128 v[78:81], v228 offset:128
	s_waitcnt lgkmcnt(3)
	s_nop 7
	v_pk_mul_f32 v[64:65], v[64:65], v[68:69]
	s_waitcnt lgkmcnt(2)
	v_pk_mul_f32 v[60:61], v[60:61], v[72:73]
	s_waitcnt lgkmcnt(1)
	v_pk_mul_f32 v[56:57], v[56:57], v[76:77]
	s_waitcnt lgkmcnt(0)
	v_pk_mul_f32 v[52:53], v[52:53], v[80:81]
	v_pk_mul_f32 v[62:63], v[62:63], v[66:67]
	v_pk_mul_f32 v[58:59], v[58:59], v[70:71]
	v_pk_mul_f32 v[54:55], v[54:55], v[74:75]
	v_pk_mul_f32 v[50:51], v[50:51], v[78:79]
	v_pk_mul_f32 v[48:49], v[48:49], v[68:69]
	v_pk_mul_f32 v[44:45], v[44:45], v[72:73]
	v_pk_mul_f32 v[40:41], v[40:41], v[76:77]
	v_pk_mul_f32 v[36:37], v[36:37], v[80:81]
	v_pk_mul_f32 v[46:47], v[46:47], v[66:67]
	v_pk_mul_f32 v[42:43], v[42:43], v[70:71]
	v_pk_mul_f32 v[38:39], v[38:39], v[74:75]
	v_pk_mul_f32 v[34:35], v[34:35], v[78:79]
	v_pk_mul_f32 v[32:33], v[32:33], v[68:69]
	v_pk_mul_f32 v[28:29], v[28:29], v[72:73]
	v_pk_mul_f32 v[24:25], v[24:25], v[76:77]
	v_pk_mul_f32 v[20:21], v[20:21], v[80:81]
	v_pk_mul_f32 v[30:31], v[30:31], v[66:67]
	v_pk_mul_f32 v[26:27], v[26:27], v[70:71]
	v_pk_mul_f32 v[22:23], v[22:23], v[74:75]
	v_pk_mul_f32 v[18:19], v[18:19], v[78:79]
	v_pk_mul_f32 v[16:17], v[16:17], v[68:69]
	v_pk_mul_f32 v[12:13], v[12:13], v[72:73]
	v_pk_mul_f32 v[8:9], v[8:9], v[76:77]
	v_pk_mul_f32 v[4:5], v[4:5], v[80:81]
	v_pk_mul_f32 v[14:15], v[14:15], v[66:67]
	v_pk_mul_f32 v[10:11], v[10:11], v[70:71]
	v_pk_mul_f32 v[6:7], v[6:7], v[74:75]
	v_pk_mul_f32 v[2:3], v[2:3], v[78:79]
.LBB0_671:
	s_lshl_b32 s26, s25, 6
	s_waitcnt lgkmcnt(0)
	s_barrier
	ds_read_b128 v[66:69], v231 offset:32768
	ds_read_b128 v[70:73], v231 offset:32784
	ds_read_b128 v[122:125], v231 offset:32832
	ds_read_b128 v[126:129], v231 offset:32848
	ds_read_b128 v[162:165], v231 offset:32896
	ds_read_b128 v[166:169], v231 offset:32912
	ds_read_b128 v[146:149], v231 offset:39424
	ds_read_b128 v[150:153], v231 offset:39440
	ds_read_b128 v[154:157], v231 offset:39488
	ds_read_b128 v[158:161], v231 offset:39504
	ds_read_b128 v[170:173], v231 offset:39552
	ds_read_b128 v[174:177], v231 offset:39568
	global_load_dwordx4 v[182:185], v[208:209], off offset:64
	s_addk_i32 s26, 0x80
	s_and_saveexec_b64 s[20:21], s[10:11]
	s_xor_b64 s[20:21], exec, s[20:21]
	s_cbranch_execz .LBB0_674
	v_or_b32_e32 v74, s26, v195
	v_ashrrev_i32_e32 v75, 31, v74
	v_lshlrev_b64 v[74:75], 6, v[74:75]
	v_lshl_add_u64 v[74:75], v[200:201], 0, v[74:75]
	v_lshl_add_u64 v[74:75], v[74:75], 0, s[92:93]
	s_andn2_saveexec_b64 s[20:21], s[20:21]
	s_cbranch_execnz .LBB0_675

; template <int MODE>
; __device__ __forceinline__ void partialSM(f32x16& p0, f32x16& p1, float& m_reg, float& mn, float& alpha, const float C, int kb, const float* btab, const bool nomask) {
;     ...
;     float pmax = p0[0];
; #pragma unroll
;     for (int r = 1; r < 16; ++r) pmax = fmaxf(pmax, p0[r]);
; #pragma unroll
;     for (int r = 0; r < 16; ++r) pmax = fmaxf(pmax, p1[r]);
;     { auto rr = __builtin_amdgcn_permlane32_swap(__float_as_uint(pmax), __float_as_uint(pmax), false, false); pmax = fmaxf(__uint_as_float(rr[0]), __uint_as_float(rr[1])); }
;     { const bool keep = __all((pmax - m_reg) * C <= (MODE == 0 ? 7.5f : 11.5f)); mn = keep ? m_reg : fmaxf(m_reg, pmax);   alpha = __builtin_amdgcn_exp2f((m_reg - mn) * C); m_reg = mn; }
;     const float mnC = -mn * C;
; #pragma unroll
;     for (int r = 0; r < 16; ++r) p0[r] = fmaf(p0[r], C, mnC);
; #pragma unroll
;     for (int r = 0; r < 16; ++r) p1[r] = fmaf(p1[r], C, mnC);
; #pragma unroll
;     for (int r = 0; r < 16; ++r) p0[r] = __builtin_amdgcn_exp2f(p0[r]);
;   }
; }
; __device__ __forceinline__ void finishSM(f32x16& p0, f32x16& p1, float alpha, float& l_reg, bf16x8& pa0, bf16x8& pa1, bf16x8& pa2, bf16x8& pa3) {
; #pragma unroll
;   for (int r = 0; r < 16; ++r) p1[r] = __builtin_amdgcn_exp2f(p1[r]);
;   float ps = 0;
; #pragma unroll
;   for (int r = 0; r < 16; ++r) ps += p0[r];
; #pragma unroll
;   for (int r = 0; r < 16; ++r) ps += p1[r];
;   { auto rr = __builtin_amdgcn_permlane32_swap(__float_as_uint(ps), __float_as_uint(ps), false, false); ps = __uint_as_float(rr[0]) + __uint_as_float(rr[1]); }
;   l_reg = l_reg * alpha + ps;
;     ...
;   PK4(p0, 0, pa0); PK4(p0, 8, pa1); PK4(p1, 0, pa2); PK4(p1, 8, pa3);
;     ...
; }
; template <int MODE>
; __device__ __forceinline__ void qkt(f32x16& p0, f32x16& p1, const char* Ks, const char* Krs, const char* Qrs, const bf16x8* qr, const i32x8* q8, int r32, int hi) {
;   p0 = f32x16{}; p1 = f32x16{};
;   if constexpr (MODE == 0) {
; #pragma unroll
;     for (int kb = 0; kb < 3; ++kb) {
; #pragma unroll
;       for (int hf = 0; hf < 2; ++hf) { const char* a_ = Ks + (hf * 32 + r32) * 208 + kb * 64 + hi * 32;
;         const u32x4 lo = *reinterpret_cast<const u32x4*>(a_), h4 = *reinterpret_cast<const u32x4*>(a_ + 16);
;         const i32x8 a = {(int)lo.x, (int)lo.y, (int)lo.z, (int)lo.w, (int)h4.x, (int)h4.y, (int)h4.z, (int)h4.w};
.LBB0_681:
	s_or_b64 exec, exec, s[20:21]
	s_waitcnt lgkmcnt(10)
	v_mfma_scale_f32_32x32x64_f8f6f4 v[66:81], v[66:73], v[114:121], 0, v216, v216 op_sel_hi:[0,0,0]
	v_exp_f32_e32 v243, v98
	v_exp_f32_e32 v244, v99
	v_exp_f32_e32 v241, v100
	v_exp_f32_e32 v242, v101
	v_exp_f32_e32 v247, v102
	v_exp_f32_e32 v248, v103
	v_add_f32_e32 v239, 0, v82
	v_add_f32_e32 v239, v83, v239
	s_waitcnt lgkmcnt(8)
	v_mfma_scale_f32_32x32x64_f8f6f4 v[66:81], v[122:129], v[130:137], v[66:81], v216, v216 op_sel_hi:[0,0,0]
	v_exp_f32_e32 v245, v104
	v_exp_f32_e32 v246, v105
	v_exp_f32_e32 v249, v106
	v_exp_f32_e32 v252, v107
	v_exp_f32_e32 v250, v108
	v_exp_f32_e32 v251, v109
	v_add_f32_e32 v239, v84, v239
	v_add_f32_e32 v239, v85, v239
	s_waitcnt lgkmcnt(6)
	v_mfma_scale_f32_32x32x64_f8f6f4 v[66:81], v[162:169], v[138:145], v[66:81], v216, v216 op_sel_hi:[0,0,0]
	v_exp_f32_e32 v254, v110
	v_exp_f32_e32 v191, v111
	v_exp_f32_e32 v253, v112
	v_exp_f32_e32 v217, v113
	v_add_f32_e32 v239, v86, v239
	v_add_f32_e32 v239, v87, v239
	v_add_f32_e32 v239, v88, v239
	v_add_f32_e32 v239, v89, v239
	v_add_f32_e32 v239, v90, v239
	v_add_f32_e32 v239, v91, v239
	s_waitcnt lgkmcnt(4)
	v_mfma_scale_f32_32x32x64_f8f6f4 v[98:113], v[146:153], v[114:121], 0, v216, v216 op_sel_hi:[0,0,0]
	v_add_f32_e32 v239, v92, v239
	v_add_f32_e32 v239, v93, v239
	v_add_f32_e32 v239, v94, v239
	v_add_f32_e32 v239, v95, v239
	v_add_f32_e32 v239, v96, v239
	v_add_f32_e32 v239, v97, v239
	v_add_f32_e32 v239, v243, v239
	v_add_f32_e32 v239, v244, v239
	v_add_f32_e32 v239, v241, v239
	v_add_f32_e32 v239, v242, v239
	v_add_f32_e32 v239, v247, v239
	s_waitcnt lgkmcnt(2)
	v_mfma_scale_f32_32x32x64_f8f6f4 v[98:113], v[154:161], v[130:137], v[98:113], v216, v216 op_sel_hi:[0,0,0]
	v_add_f32_e32 v239, v248, v239
	v_add_f32_e32 v239, v245, v239
	v_add_f32_e32 v239, v246, v239
	v_add_f32_e32 v239, v249, v239
	v_add_f32_e32 v239, v252, v239
	v_add_f32_e32 v239, v250, v239
	v_add_f32_e32 v239, v251, v239
	v_add_f32_e32 v239, v254, v239
	v_add_f32_e32 v239, v191, v239
	v_add_f32_e32 v239, v253, v239
	s_waitcnt lgkmcnt(0)
	v_mfma_scale_f32_32x32x64_f8f6f4 v[98:113], v[170:177], v[138:145], v[98:113], v216, v216 op_sel_hi:[0,0,0]
	s_nop 0
	v_add_f32_e32 v239, v217, v239
	v_mov_b32_e32 v240, v239
	s_nop 1
	v_permlane32_swap_b32_e32 v239, v240
	ds_read_b128 v[154:157], v230 offset:16384
	ds_read_b128 v[158:161], v230 offset:16400
	ds_read_b128 v[146:149], v230 offset:18944
	ds_read_b128 v[150:153], v230 offset:18960
	ds_read_b128 v[122:125], v230 offset:21504
	ds_read_b128 v[126:129], v230 offset:21520
	ds_read_b128 v[166:169], v230 offset:24080
	s_nop 3
	v_max_f32_e32 v162, v67, v67
	v_max_f32_e32 v163, v66, v66
	v_max_f32_e32 v162, v163, v162
	v_max3_f32 v162, v162, v68, v69
	v_max3_f32 v162, v162, v70, v71
	v_max3_f32 v162, v162, v72, v73
	v_max3_f32 v162, v162, v74, v75
	v_max3_f32 v162, v162, v76, v77
	v_max3_f32 v162, v162, v78, v79
	v_max3_f32 v162, v162, v80, v81
	v_max3_f32 v162, v162, v98, v99
	v_max3_f32 v162, v162, v100, v101
	v_max3_f32 v162, v162, v102, v103
	v_max3_f32 v162, v162, v104, v105
	v_max3_f32 v162, v162, v106, v107
	v_max3_f32 v162, v162, v108, v109
	v_max3_f32 v162, v162, v110, v111
	v_max3_f32 v162, v162, v112, v113
	v_mov_b32_e32 v163, v162
	s_nop 1
	v_permlane32_swap_b32_e32 v162, v163
	v_max_f32_e32 v163, v163, v163
	v_max_f32_e32 v162, v162, v162
	v_max_f32_e32 v162, v162, v163
	v_sub_f32_e32 v163, v162, v238
	v_mul_f32_e32 v163, 0x3dd53b94, v163
	v_cmp_ge_f32_e32 vcc, s57, v163
	s_cmp_eq_u64 vcc, exec
	v_max_f32_e32 v163, v238, v238
	s_cselect_b64 vcc, -1, 0
	v_max_f32_e32 v162, v163, v162
	v_cndmask_b32_e32 v237, v162, v238, vcc
	v_sub_f32_e32 v170, v238, v237
	v_mul_f32_e32 v170, 0x3dd53b94, v170
	v_exp_f32_e32 v170, v170
	ds_read_b128 v[162:165], v230 offset:24064
	s_waitcnt lgkmcnt(0)
	s_barrier
; __device__ __forceinline__ unsigned pk4_fp8(float a, float b, float c, float d) { int p = __builtin_amdgcn_cvt_pk_fp8_f32(a, b, 0, false); p = __builtin_amdgcn_cvt_pk_fp8_f32(c, d, p, true); return (unsigned)p; }
; #define SBAR() __builtin_amdgcn_sched_barrier(0)
; #define PVC(voff) do { if constexpr (MODE == 0) pv8(o, V_lds + (voff), pa0, pa1, r32, hi); else pv_d0(o, vb0 + (voff), pa0, pa1, pa2, pa3); } while (0)
; #define SWAIT() do { if constexpr (SD == 1) asm volatile("s_waitcnt vmcnt(0)" ::: "memory"); else if constexpr (MODE == 0) asm volatile("s_waitcnt vmcnt(5)" ::: "memory"); else asm volatile("s_waitcnt vmcnt(4)" ::: "memory"); } while (0)
; __device__ __forceinline__ void finishSM8(f32x16& p0, f32x16& p1, float alpha, float& l_reg, bf16x8& pa0, bf16x8& pa1) {
;     ...
;   const u32x4 w0 = {pk4_fp8(p0[0], p0[1], p0[2], p0[3]), pk4_fp8(p0[4], p0[5], p0[6], p0[7]), pk4_fp8(p0[8], p0[9], p0[10], p0[11]), pk4_fp8(p0[12], p0[13], p0[14], p0[15])};
;   const u32x4 w1 = {pk4_fp8(p1[0], p1[1], p1[2], p1[3]), pk4_fp8(p1[4], p1[5], p1[6], p1[7]), pk4_fp8(p1[8], p1[9], p1[10], p1[11]), pk4_fp8(p1[12], p1[13], p1[14], p1[15])};
;   pa0 = __builtin_bit_cast(bf16x8, w0); pa1 = __builtin_bit_cast(bf16x8, w1);
; }
; __device__ __forceinline__ void pv8(f32x16* o, const char* Vs, bf16x8 pa0, bf16x8 pa1, int r32, int hi) {
;   const u32x4 a0 = __builtin_bit_cast(u32x4, pa0), a1 = __builtin_bit_cast(u32x4, pa1);
;   const i32x8 P = {(int)a0.x, (int)a0.y, (int)a0.z, (int)a0.w, (int)a1.x, (int)a1.y, (int)a1.z, (int)a1.w};
; #pragma unroll
;   for (int d0 = 0; d0 < 4; ++d0) { const char* b_ = Vs + (d0 * 32 + r32) * 80 + hi * 32;
;     const u32x4 lo = *reinterpret_cast<const u32x4*>(b_), h4 = *reinterpret_cast<const u32x4*>(b_ + 16);
;     const i32x8 V = {(int)lo.x, (int)lo.y, (int)lo.z, (int)lo.w, (int)h4.x, (int)h4.y, (int)h4.z, (int)h4.w};
;     o[d0] = __builtin_amdgcn_mfma_scale_f32_32x32x64_f8f6f4(P, V, o[d0], 0, 0, 0, 0x7F7F7F7F, 0, 0x7F7F7F7F); }
; template <int MODE, int SD> ...
;     ...
;     PVC(SHM_V); partialSM<MODE>(pA0, pA1, m_reg, mnA, alA, C, kbl + (j + 1) * KVBLK, btab, nomask); asm volatile("" : "+v"(pA0), "+v"(pA1), "+v"(alA)); SG_PV(); SBAR();
;     __syncthreads(); SWAIT(); SWRITE(1, SO);
;     RESC(alA); __syncthreads();
;   }
	s_waitcnt vmcnt(0)
	s_waitcnt vmcnt(1)
	ds_write_b128 v225, v[182:185] offset:16384
	s_waitcnt vmcnt(0)
	ds_write_b128 v226, v[186:189] offset:49152
	s_and_saveexec_b64 s[20:21], s[12:13]
	ds_write_b128 v234, v[178:181] offset:49152
	s_or_b64 exec, exec, s[20:21]
	v_mul_f32_e32 v172, 0xbdd53b94, v237
	v_mov_b32_e32 v182, 0
	v_mov_b32_e32 v183, 0
	v_mov_b32_e32 v184, 0
	v_mov_b32_e32 v185, 0
	v_mov_b32_e32 v186, 0
	v_mov_b32_e32 v187, 0
	v_mov_b32_e32 v188, 0
	v_mov_b32_e32 v189, 0
	v_cvt_pk_fp8_f32 v182, v82, v83
	v_cvt_pk_fp8_f32 v183, v86, v87
	v_cvt_pk_fp8_f32 v184, v90, v91
	v_cvt_pk_fp8_f32 v185, v94, v95
	v_cvt_pk_fp8_f32 v186, v243, v244
	v_cvt_pk_fp8_f32 v187, v247, v248
	v_cvt_pk_fp8_f32 v188, v249, v252
	v_cvt_pk_fp8_f32 v189, v254, v191
	v_cvt_pk_fp8_f32 v182, v84, v85 op_sel:[0,0,1]
	v_cvt_pk_fp8_f32 v183, v88, v89 op_sel:[0,0,1]
	v_cvt_pk_fp8_f32 v184, v92, v93 op_sel:[0,0,1]
	v_cvt_pk_fp8_f32 v185, v96, v97 op_sel:[0,0,1]
	v_cvt_pk_fp8_f32 v186, v241, v242 op_sel:[0,0,1]
	v_cvt_pk_fp8_f32 v187, v245, v246 op_sel:[0,0,1]
	v_cvt_pk_fp8_f32 v188, v250, v251 op_sel:[0,0,1]
	v_cvt_pk_fp8_f32 v189, v253, v217 op_sel:[0,0,1]
	v_cmp_gt_f32_e32 vcc, 1.0, v170
	s_nop 0
	v_mfma_scale_f32_32x32x64_f8f6f4 v[50:65], v[182:189], v[154:161], v[50:65], v216, v216 op_sel_hi:[0,0,0]
	v_fmamk_f32 v66, v66, 0x3dd53b94, v172
	v_exp_f32_e32 v66, v66
	v_fmamk_f32 v67, v67, 0x3dd53b94, v172
	v_exp_f32_e32 v67, v67
	v_fmamk_f32 v68, v68, 0x3dd53b94, v172
	v_exp_f32_e32 v68, v68
	v_fmamk_f32 v69, v69, 0x3dd53b94, v172
	v_exp_f32_e32 v69, v69
	v_mfma_scale_f32_32x32x64_f8f6f4 v[34:49], v[182:189], v[146:153], v[34:49], v216, v216 op_sel_hi:[0,0,0]
	v_fmamk_f32 v70, v70, 0x3dd53b94, v172
	v_exp_f32_e32 v70, v70
	v_fmamk_f32 v71, v71, 0x3dd53b94, v172
	v_exp_f32_e32 v71, v71
	v_fmamk_f32 v72, v72, 0x3dd53b94, v172
	v_exp_f32_e32 v72, v72
	v_fmamk_f32 v73, v73, 0x3dd53b94, v172
	v_exp_f32_e32 v73, v73
	v_mfma_scale_f32_32x32x64_f8f6f4 v[18:33], v[182:189], v[122:129], v[18:33], v216, v216 op_sel_hi:[0,0,0]
	v_fmamk_f32 v74, v74, 0x3dd53b94, v172
	v_exp_f32_e32 v74, v74
	v_fmamk_f32 v75, v75, 0x3dd53b94, v172
	v_exp_f32_e32 v75, v75
	v_fmamk_f32 v76, v76, 0x3dd53b94, v172
	v_exp_f32_e32 v76, v76
	v_fmamk_f32 v77, v77, 0x3dd53b94, v172
	v_exp_f32_e32 v77, v77
	v_mfma_scale_f32_32x32x64_f8f6f4 v[2:17], v[182:189], v[162:169], v[2:17], v216, v216 op_sel_hi:[0,0,0]
	v_fmamk_f32 v78, v78, 0x3dd53b94, v172
	v_exp_f32_e32 v78, v78
	v_fmamk_f32 v79, v79, 0x3dd53b94, v172
	v_exp_f32_e32 v79, v79
	v_fmamk_f32 v80, v80, 0x3dd53b94, v172
	v_exp_f32_e32 v80, v80
	v_fmamk_f32 v81, v81, 0x3dd53b94, v172
	v_exp_f32_e32 v81, v81
	v_pk_fma_f32 v[98:99], v[98:99], s[78:79], v[172:173] op_sel_hi:[1,0,0]
	v_pk_fma_f32 v[100:101], v[100:101], s[78:79], v[172:173] op_sel_hi:[1,0,0]
	v_pk_fma_f32 v[102:103], v[102:103], s[78:79], v[172:173] op_sel_hi:[1,0,0]
	v_pk_fma_f32 v[104:105], v[104:105], s[78:79], v[172:173] op_sel_hi:[1,0,0]
	v_pk_fma_f32 v[106:107], v[106:107], s[78:79], v[172:173] op_sel_hi:[1,0,0]
	v_pk_fma_f32 v[108:109], v[108:109], s[78:79], v[172:173] op_sel_hi:[1,0,0]
	v_pk_fma_f32 v[110:111], v[110:111], s[78:79], v[172:173] op_sel_hi:[1,0,0]
	v_pk_fma_f32 v[112:113], v[112:113], s[78:79], v[172:173] op_sel_hi:[1,0,0]
	s_cbranch_vccz .LBB0_654
	s_and_saveexec_b64 s[20:21], s[8:9]
	s_cbranch_execz .LBB0_653
	ds_write_b32 v229, v170 offset:128
	s_branch .LBB0_653
